# v6 + panel-group (16-WG) barriers at seams 5-8 + persistent 10us parity stagger after attention + W_out epilogue rolling prefetch
# speedup vs baseline: 1.0110x; 1.0110x over previous
; __device__ __forceinline__ void xcd_barrier(const XcdBarrier& b) {
;     ...
;     }
;     __syncthreads();
; }
.LBB0_765:
	s_or_b64 exec, exec, s[8:9]
	s_bfe_u32 s4, s2, 0x10003
	s_cmp_eq_u32 s4, 0
	s_cbranch_scc1 .Lstag_skip
	s_movk_i32 s10, 3
.Lstag_loop:
	s_sleep 127
	s_sub_i32 s10, s10, 1
	s_cmp_gt_i32 s10, 0
	s_cbranch_scc1 .Lstag_loop
.Lstag_skip:
	s_lshl_b32 s4, s84, 5
	s_and_b32 s70, s4, 0x60
	s_lshr_b32 s71, s70, 3
	s_cmpk_lt_i32 s2, 0x100
	s_movk_i32 s12, 0x200
	s_movk_i32 s8, 0x200
	s_cselect_b64 s[14:15], -1, 0
	s_cmpk_gt_i32 s2, 0xff
	s_waitcnt lgkmcnt(0)
	s_barrier
	v_mbcnt_lo_u32_b32 v12, -1, 0
	v_mbcnt_hi_u32_b32 v12, -1, v12
	s_cbranch_scc1 .LBB0_794
	s_cmp_gt_i32 s89, -1
	s_cbranch_scc0 .LBB0_768
	s_lshl_b32 s9, s89, 5
	s_cbranch_execz .LBB0_769
	s_branch .LBB0_770

; __device__ __forceinline__ unsigned xb_ld(unsigned* p)              { return __hip_atomic_load(p, __ATOMIC_RELAXED, __HIP_MEMORY_SCOPE_AGENT); }
; __device__ __forceinline__ unsigned xb_add(unsigned* p, unsigned v) { return __hip_atomic_fetch_add(p, v, __ATOMIC_RELAXED, __HIP_MEMORY_SCOPE_AGENT); }
; #define XB_SPIN(cond, bar) do { unsigned _sp = 0; while (cond) { __builtin_amdgcn_s_sleep(1); \
;     if ((++_sp & 255u) == 0u) { if (xb_ld(&(bar)[XB_TMO])) break; if (_sp > XB_SPIN_CAP) { atomicAdd(&(bar)[XB_TMO], 1u); break; } } } } while (0)
; __device__ __forceinline__ void xcd_barrier(const XcdBarrier& b) {
;     asm volatile("s_waitcnt vmcnt(0)" ::: "memory");
;     __syncthreads();
;     if (threadIdx.x == 0) {
;         unsigned* bar = b.bar;
;         __builtin_amdgcn_s_waitcnt(0);
;         unsigned nloc = b.st[0], nx = b.st[1];
;         if (nloc == 0u) { xcd_barrier_complete(bar, b.x, nloc, nx); b.st[0] = nloc; b.st[1] = nx; }
;         const unsigned old = xb_add(&bar[XB_XSUB(b.x)], 1u);
;         const unsigned gen = old / nloc;
;         if (old + 1u == (gen + 1u) * nloc) {
;             __builtin_amdgcn_fence(__ATOMIC_RELEASE, "agent");
;             asm volatile("s_waitcnt vmcnt(0)" ::: "memory");
;             const unsigned og = xb_add(&bar[XB_TOP], 1u);
;             const unsigned tg = og / nx;
;             if (og + 1u == (tg + 1u) * nx) xb_add(&bar[XB_TOPGEN], 1u);
;             else XB_SPIN(xb_ld(&bar[XB_TOPGEN]) == tg, bar);
;             __builtin_amdgcn_fence(__ATOMIC_ACQUIRE, "agent");
;             xb_add(&bar[XB_XGEN(b.x)], 1u);
;             asm volatile("s_waitcnt vmcnt(0)" ::: "memory");
;         } else {
;             XB_SPIN(xb_ld(&bar[XB_XGEN(b.x)]) == gen, bar);
;             __builtin_amdgcn_fence(__ATOMIC_ACQUIRE, "agent");
;             asm volatile("s_waitcnt vmcnt(0)" ::: "memory");
;         }
;     }
;     __syncthreads();
.LBB0_823:
	s_waitcnt vmcnt(0)
	s_waitcnt lgkmcnt(0)
	s_barrier
	s_and_saveexec_b64 s[10:11], s[82:83]
	s_cbranch_execz .LBB0_875
	s_cmp_eq_u32 s99, 0
	s_cbranch_scc1 .Lgb0_orig
	s_cmpk_lg_u32 s30, 0x100
	s_cbranch_scc1 .Lgb0_orig
	s_and_b32 s12, s2, 7
	s_lshl_b32 s12, s12, 1
	s_bfe_u32 s13, s2, 0x10003
	s_or_b32 s12, s12, s13
	s_lshl_b32 s12, s12, 6
	s_add_u32 s12, s12, 0x15000
	v_mov_b32_e32 v0, s12
	v_mov_b32_e32 v1, 1
	global_atomic_add v2, v0, v1, s[28:29] sc0
	s_waitcnt vmcnt(0)
	v_and_b32_e32 v4, 15, v2
	v_lshrrev_b32_e32 v2, 4, v2
	v_cmp_ne_u32_e32 vcc, 15, v4
	s_nop 1
	s_cbranch_vccnz .Lgb0_spin
	global_atomic_add v0, v1, s[28:29] offset:1024
	s_branch .Lgb0_done
.Lgb0_spin:
	global_load_dword v4, v0, s[28:29] offset:1024 sc1
	s_waitcnt vmcnt(0)
	v_cmp_gt_u32_e32 vcc, v4, v2
	s_nop 1
	s_cbranch_vccnz .Lgb0_done
	s_sleep 1
	s_branch .Lgb0_spin
.Lgb0_done:
	buffer_inv sc1
	s_waitcnt vmcnt(0)
	s_branch .LBB0_875
.Lgb0_orig:
	s_add_i32 s4, 0, 0x243c0
	v_mov_b32_e32 v0, s4
	s_waitcnt vmcnt(0) expcnt(0) lgkmcnt(0)
	ds_read_b32 v2, v0
	s_add_i32 s4, 0, 0x243c4
	v_mov_b32_e32 v0, s4
	ds_read_b32 v0, v0
	s_waitcnt lgkmcnt(1)
	v_cmp_ne_u32_e32 vcc, 0, v2
	s_cbranch_vccnz .LBB0_839
	s_add_u32 s12, s28, 0x10200
	s_addc_u32 s13, s29, 0
	s_add_u32 s14, s28, 0x10400
	s_addc_u32 s15, s29, 0
	s_add_u32 s16, s28, 0x10500
	s_addc_u32 s17, s29, 0
	s_add_u32 s18, s28, 0x10600
	s_addc_u32 s19, s29, 0
	s_add_u32 s20, s28, 0x10700
	s_addc_u32 s21, s29, 0
	s_add_u32 s22, s28, 0x10800
	s_addc_u32 s23, s29, 0
	s_add_u32 s24, s28, 0x10900
	s_addc_u32 s25, s29, 0
	s_add_u32 s26, s28, 0x10a00
	s_addc_u32 s27, s29, 0
	s_add_u32 s44, s28, 0x10b00
	s_addc_u32 s45, s29, 0
	s_add_u32 s46, s28, 0x10c00
	s_addc_u32 s47, s29, 0
	s_add_u32 s48, s28, 0x10d00
	s_addc_u32 s49, s29, 0
	s_add_u32 s50, s28, 0x10e00
	s_addc_u32 s51, s29, 0
	s_add_u32 s52, s28, 0x10f00
	s_addc_u32 s53, s29, 0
	s_add_u32 s54, s28, 0x11000
	s_load_dword s4, s[0:1], 0xb8
	s_addc_u32 s55, s29, 0
	s_add_u32 s56, s28, 0x11100
	s_addc_u32 s57, s29, 0
	s_add_u32 s58, s28, 0x11200
	s_addc_u32 s59, s29, 0
	s_waitcnt lgkmcnt(0)
	s_mul_i32 s4, s31, s4
	s_add_u32 s60, s28, 0x11300
	s_mul_i32 s4, s4, s30
	s_addc_u32 s61, s29, 0
	s_mov_b32 s5, 1
	v_mov_b32_e32 v16, 0
	s_branch .LBB0_827

; __device__ __forceinline__ unsigned xb_ld(unsigned* p)              { return __hip_atomic_load(p, __ATOMIC_RELAXED, __HIP_MEMORY_SCOPE_AGENT); }
; __device__ __forceinline__ void xcd_barrier_complete(unsigned* bar, unsigned x, unsigned& nloc, unsigned& nx) {
;     const unsigned G = gridDim.x * gridDim.y * gridDim.z;
;     unsigned sum, cnt, mine, sp = 0u;
;     for (;;) {
;         sum = 0u; cnt = 0u; mine = 0u;
; #pragma unroll
;         for (unsigned j = 0; j < 16; ++j) { const unsigned c = xb_ld(&bar[XB_XCNT(j)]); sum += c; cnt += (c > 0u) ? 1u : 0u; mine = (j == x) ? c : mine; }
; __device__ __forceinline__ void xcd_barrier(const XcdBarrier& b) {
;     ...
;         unsigned* bar = b.bar;
;         __builtin_amdgcn_s_waitcnt(0);
;         unsigned nloc = b.st[0], nx = b.st[1];
;         if (nloc == 0u) { xcd_barrier_complete(bar, b.x, nloc, nx); b.st[0] = nloc; b.st[1] = nx; }
.Lgb1_orig:
	s_add_i32 s4, 0, 0x243c0
	v_mov_b32_e32 v0, s4
	s_waitcnt vmcnt(0) expcnt(0) lgkmcnt(0)
	ds_read_b32 v2, v0
	s_add_i32 s4, 0, 0x243c4
	v_mov_b32_e32 v0, s4
	ds_read_b32 v0, v0
	s_waitcnt lgkmcnt(1)
	v_cmp_ne_u32_e32 vcc, 0, v2
	s_cbranch_vccnz .LBB0_938
	s_add_u32 s12, s28, 0x10200
	s_addc_u32 s13, s29, 0
	s_add_u32 s14, s28, 0x10400
	s_addc_u32 s15, s29, 0
	s_add_u32 s18, s28, 0x10500
	s_addc_u32 s19, s29, 0
	s_add_u32 s20, s28, 0x10600
	s_addc_u32 s21, s29, 0
	s_add_u32 s22, s28, 0x10700
	s_addc_u32 s23, s29, 0
	s_add_u32 s24, s28, 0x10800
	s_addc_u32 s25, s29, 0
	s_add_u32 s26, s28, 0x10900
	s_addc_u32 s27, s29, 0
	s_add_u32 s44, s28, 0x10a00
	s_addc_u32 s45, s29, 0
	s_add_u32 s46, s28, 0x10b00
	s_addc_u32 s47, s29, 0
	s_add_u32 s48, s28, 0x10c00
	s_addc_u32 s49, s29, 0
	s_add_u32 s50, s28, 0x10d00
	s_addc_u32 s51, s29, 0
	s_add_u32 s52, s28, 0x10e00
	s_addc_u32 s53, s29, 0
	s_add_u32 s54, s28, 0x10f00
	s_addc_u32 s55, s29, 0
	s_add_u32 s56, s28, 0x11000
	s_load_dword s4, s[0:1], 0xb8
	s_addc_u32 s57, s29, 0
	s_add_u32 s58, s28, 0x11100
	s_addc_u32 s59, s29, 0
	s_add_u32 s60, s28, 0x11200
	s_addc_u32 s61, s29, 0
	s_waitcnt lgkmcnt(0)
	s_mul_i32 s4, s31, s4
	s_add_u32 s62, s28, 0x11300
	s_mul_i32 s4, s4, s30
	s_addc_u32 s63, s29, 0
	s_mov_b32 s5, 1
	v_mov_b32_e32 v16, 0
	s_branch .LBB0_926

; __device__ __forceinline__ unsigned xb_ld(unsigned* p)              { return __hip_atomic_load(p, __ATOMIC_RELAXED, __HIP_MEMORY_SCOPE_AGENT); }
; __device__ __forceinline__ unsigned xb_add(unsigned* p, unsigned v) { return __hip_atomic_fetch_add(p, v, __ATOMIC_RELAXED, __HIP_MEMORY_SCOPE_AGENT); }
; #define XB_SPIN(cond, bar) do { unsigned _sp = 0; while (cond) { __builtin_amdgcn_s_sleep(1); \
;     if ((++_sp & 255u) == 0u) { if (xb_ld(&(bar)[XB_TMO])) break; if (_sp > XB_SPIN_CAP) { atomicAdd(&(bar)[XB_TMO], 1u); break; } } } } while (0)
; __device__ __forceinline__ void xcd_barrier(const XcdBarrier& b) {
;     asm volatile("s_waitcnt vmcnt(0)" ::: "memory");
;     __syncthreads();
;     if (threadIdx.x == 0) {
;         unsigned* bar = b.bar;
;         __builtin_amdgcn_s_waitcnt(0);
;         unsigned nloc = b.st[0], nx = b.st[1];
;         if (nloc == 0u) { xcd_barrier_complete(bar, b.x, nloc, nx); b.st[0] = nloc; b.st[1] = nx; }
;         const unsigned old = xb_add(&bar[XB_XSUB(b.x)], 1u);
;         const unsigned gen = old / nloc;
;         if (old + 1u == (gen + 1u) * nloc) {
;             __builtin_amdgcn_fence(__ATOMIC_RELEASE, "agent");
;             asm volatile("s_waitcnt vmcnt(0)" ::: "memory");
;             const unsigned og = xb_add(&bar[XB_TOP], 1u);
;             const unsigned tg = og / nx;
;             if (og + 1u == (tg + 1u) * nx) xb_add(&bar[XB_TOPGEN], 1u);
;             else XB_SPIN(xb_ld(&bar[XB_TOPGEN]) == tg, bar);
;             __builtin_amdgcn_fence(__ATOMIC_ACQUIRE, "agent");
;             xb_add(&bar[XB_XGEN(b.x)], 1u);
;             asm volatile("s_waitcnt vmcnt(0)" ::: "memory");
;         } else {
;             XB_SPIN(xb_ld(&bar[XB_XGEN(b.x)]) == gen, bar);
;             __builtin_amdgcn_fence(__ATOMIC_ACQUIRE, "agent");
;             asm volatile("s_waitcnt vmcnt(0)" ::: "memory");
;         }
;     }
;     __syncthreads();
.LBB0_1025:
	s_waitcnt vmcnt(0)
	s_waitcnt vmcnt(0) lgkmcnt(0)
	s_barrier
	s_and_saveexec_b64 s[10:11], s[82:83]
	s_cbranch_execz .LBB0_1077
	s_cmp_eq_u32 s99, 0
	s_cbranch_scc1 .Lgb2_orig
	s_cmpk_lg_u32 s30, 0x100
	s_cbranch_scc1 .Lgb2_orig
	s_and_b32 s12, s2, 7
	s_lshl_b32 s12, s12, 1
	s_bfe_u32 s13, s2, 0x10003
	s_or_b32 s12, s12, s13
	s_lshl_b32 s12, s12, 6
	s_add_u32 s12, s12, 0x15000
	v_mov_b32_e32 v0, s12
	v_mov_b32_e32 v1, 1
	global_atomic_add v2, v0, v1, s[28:29] sc0
	s_waitcnt vmcnt(0)
	v_and_b32_e32 v4, 15, v2
	v_lshrrev_b32_e32 v2, 4, v2
	v_cmp_ne_u32_e32 vcc, 15, v4
	s_nop 1
	s_cbranch_vccnz .Lgb2_spin
	global_atomic_add v0, v1, s[28:29] offset:1024
	s_branch .Lgb2_done

; __device__ __forceinline__ unsigned xb_ld(unsigned* p)              { return __hip_atomic_load(p, __ATOMIC_RELAXED, __HIP_MEMORY_SCOPE_AGENT); }
; __device__ __forceinline__ void xcd_barrier_complete(unsigned* bar, unsigned x, unsigned& nloc, unsigned& nx) {
;     const unsigned G = gridDim.x * gridDim.y * gridDim.z;
;     unsigned sum, cnt, mine, sp = 0u;
;     for (;;) {
;         sum = 0u; cnt = 0u; mine = 0u;
; #pragma unroll
;         for (unsigned j = 0; j < 16; ++j) { const unsigned c = xb_ld(&bar[XB_XCNT(j)]); sum += c; cnt += (c > 0u) ? 1u : 0u; mine = (j == x) ? c : mine; }
; __device__ __forceinline__ void xcd_barrier(const XcdBarrier& b) {
;     ...
;         unsigned* bar = b.bar;
;         __builtin_amdgcn_s_waitcnt(0);
;         unsigned nloc = b.st[0], nx = b.st[1];
;         if (nloc == 0u) { xcd_barrier_complete(bar, b.x, nloc, nx); b.st[0] = nloc; b.st[1] = nx; }
.Lgb2_orig:
	s_add_i32 s4, 0, 0x243c0
	v_mov_b32_e32 v0, s4
	s_waitcnt vmcnt(0) expcnt(0) lgkmcnt(0)
	ds_read_b32 v2, v0
	s_add_i32 s4, 0, 0x243c4
	v_mov_b32_e32 v0, s4
	ds_read_b32 v0, v0
	s_waitcnt lgkmcnt(1)
	v_cmp_ne_u32_e32 vcc, 0, v2
	s_cbranch_vccnz .LBB0_1041
	s_add_u32 s12, s28, 0x10200
	s_addc_u32 s13, s29, 0
	s_add_u32 s14, s28, 0x10400
	s_addc_u32 s15, s29, 0
	s_add_u32 s16, s28, 0x10500
	s_addc_u32 s17, s29, 0
	s_add_u32 s18, s28, 0x10600
	s_addc_u32 s19, s29, 0
	s_add_u32 s22, s28, 0x10700
	s_addc_u32 s23, s29, 0
	s_add_u32 s24, s28, 0x10800
	s_addc_u32 s25, s29, 0
	s_add_u32 s26, s28, 0x10900
	s_addc_u32 s27, s29, 0
	s_add_u32 s42, s28, 0x10a00
	s_addc_u32 s43, s29, 0
	s_add_u32 s44, s28, 0x10b00
	s_addc_u32 s45, s29, 0
	s_add_u32 s46, s28, 0x10c00
	s_addc_u32 s47, s29, 0
	s_add_u32 s48, s28, 0x10d00
	s_addc_u32 s49, s29, 0
	s_add_u32 s50, s28, 0x10e00
	s_addc_u32 s51, s29, 0
	s_add_u32 s52, s28, 0x10f00
	s_addc_u32 s53, s29, 0
	s_add_u32 s54, s28, 0x11000
	s_load_dword s4, s[0:1], 0xb8
	s_addc_u32 s55, s29, 0
	s_add_u32 s56, s28, 0x11100
	s_addc_u32 s57, s29, 0
	s_add_u32 s58, s28, 0x11200
	s_addc_u32 s59, s29, 0
	s_waitcnt lgkmcnt(0)
	s_mul_i32 s4, s31, s4
	s_add_u32 s60, s28, 0x11300
	s_mul_i32 s4, s4, s30
	s_addc_u32 s61, s29, 0
	s_mov_b32 s5, 1
	v_mov_b32_e32 v16, 0
	s_branch .LBB0_1029

; __device__ __forceinline__ unsigned xb_ld(unsigned* p)              { return __hip_atomic_load(p, __ATOMIC_RELAXED, __HIP_MEMORY_SCOPE_AGENT); }
; __device__ __forceinline__ void xcd_barrier_complete(unsigned* bar, unsigned x, unsigned& nloc, unsigned& nx) {
;     const unsigned G = gridDim.x * gridDim.y * gridDim.z;
;     unsigned sum, cnt, mine, sp = 0u;
;     for (;;) {
;         sum = 0u; cnt = 0u; mine = 0u;
; #pragma unroll
;         for (unsigned j = 0; j < 16; ++j) { const unsigned c = xb_ld(&bar[XB_XCNT(j)]); sum += c; cnt += (c > 0u) ? 1u : 0u; mine = (j == x) ? c : mine; }
; __device__ __forceinline__ void xcd_barrier(const XcdBarrier& b) {
;     ...
;         unsigned* bar = b.bar;
;         __builtin_amdgcn_s_waitcnt(0);
;         unsigned nloc = b.st[0], nx = b.st[1];
;         if (nloc == 0u) { xcd_barrier_complete(bar, b.x, nloc, nx); b.st[0] = nloc; b.st[1] = nx; }
.Lgb3_orig:
	s_add_i32 s4, 0, 0x243c0
	v_mov_b32_e32 v0, s4
	s_waitcnt vmcnt(0) expcnt(0) lgkmcnt(0)
	ds_read_b32 v2, v0
	s_add_i32 s4, 0, 0x243c4
	v_mov_b32_e32 v0, s4
	ds_read_b32 v0, v0
	s_waitcnt lgkmcnt(1)
	v_cmp_ne_u32_e32 vcc, 0, v2
	s_cbranch_vccnz .LBB0_1140
	s_load_dword s4, s[0:1], 0xb8
	s_mov_b32 s62, 1
	v_mov_b32_e32 v16, 0
	s_waitcnt lgkmcnt(0)
	s_mul_i32 s33, s31, s4
	s_add_u32 s4, s28, 0x10200
	s_addc_u32 s5, s29, 0
	s_add_u32 s12, s28, 0x10400
	s_addc_u32 s13, s29, 0
	s_add_u32 s14, s28, 0x10500
	s_addc_u32 s15, s29, 0
	s_add_u32 s16, s28, 0x10600
	s_addc_u32 s17, s29, 0
	s_add_u32 s20, s28, 0x10700
	s_addc_u32 s21, s29, 0
	s_add_u32 s22, s28, 0x10800
	s_addc_u32 s23, s29, 0
	s_add_u32 s24, s28, 0x10900
	s_addc_u32 s25, s29, 0
	s_add_u32 s26, s28, 0x10a00
	s_addc_u32 s27, s29, 0
	s_mul_i32 s33, s33, s30
	s_add_u32 s30, s28, 0x10b00
	s_addc_u32 s31, s29, 0
	s_add_u32 s40, s28, 0x10c00
	s_addc_u32 s41, s29, 0
	s_add_u32 s42, s28, 0x10d00
	s_addc_u32 s43, s29, 0
	s_add_u32 s44, s28, 0x10e00
	s_addc_u32 s45, s29, 0
	s_add_u32 s46, s28, 0x10f00
	s_addc_u32 s47, s29, 0
	s_add_u32 s48, s28, 0x11000
	s_addc_u32 s49, s29, 0
	s_add_u32 s50, s28, 0x11100
	s_addc_u32 s51, s29, 0
	s_add_u32 s52, s28, 0x11200
	s_addc_u32 s53, s29, 0
	s_add_u32 s54, s28, 0x11300
	s_addc_u32 s55, s29, 0
	s_branch .LBB0_1128
